# grid barrier: XCD leader releases local workgroups before its own L1 invalidate (buffer_inv moved after the XGEN atomic)
# baseline (speedup 1.0000x reference)
.LBB0_375:
	s_or_b64 exec, exec, s[6:7]
	buffer_inv sc1
	s_waitcnt vmcnt(0)

.LBB0_442:
	s_or_b64 exec, exec, s[4:5]
	s_mov_b64 s[4:5], exec
	v_mbcnt_lo_u32_b32 v0, s4, 0
	v_mbcnt_hi_u32_b32 v0, s5, v0
	v_cmp_eq_u32_e32 vcc, 0, v0
	s_waitcnt vmcnt(0)
	s_and_saveexec_b64 s[10:11], vcc
	s_cbranch_execz .LBB0_444
	s_bcnt1_i32_b64 s4, s[4:5]
	v_mov_b32_e32 v0, s4
	v_mov_b32_e32 v2, 0x2000
	global_atomic_add v2, v0, s[6:7] offset:1024
.LBB0_444:
	s_or_b64 exec, exec, s[10:11]
	buffer_inv sc1
	s_waitcnt vmcnt(0)

.LBB0_537:
	s_or_b64 exec, exec, s[2:3]
	s_mov_b64 s[2:3], exec
	v_mbcnt_lo_u32_b32 v0, s2, 0
	v_mbcnt_hi_u32_b32 v0, s3, v0
	v_cmp_eq_u32_e32 vcc, 0, v0
	s_waitcnt vmcnt(0)
	s_and_saveexec_b64 s[6:7], vcc
	s_cbranch_execz .LBB0_539
	s_bcnt1_i32_b64 s2, s[2:3]
	v_mov_b32_e32 v0, s2
	v_mov_b32_e32 v2, 0x2000
	global_atomic_add v2, v0, s[4:5] offset:1024

.LBB0_1930:
	s_or_b64 exec, exec, s[2:3]
	s_mov_b64 s[2:3], exec
	v_mbcnt_lo_u32_b32 v0, s2, 0
	v_mbcnt_hi_u32_b32 v0, s3, v0
	v_cmp_eq_u32_e32 vcc, 0, v0
	s_waitcnt vmcnt(0)
	s_and_saveexec_b64 s[6:7], vcc
	s_cbranch_execnz .LBB0_1931
	s_getpc_b64 s[98:99]
